# deferral split: w_glu+w_mkv transposes at P1 head, w_out0 transposes at P3 head (odd XCDs), rest of stack8
# speedup vs baseline: 1.0145x; 1.0145x over previous
.LBB0_30:
	s_cmp_eq_u32 s100, 1
	s_cbranch_scc1 .Ldf_ret_p1
	s_cmp_eq_u32 s100, 2
	s_cbranch_scc1 .Ldf_ret_p3
	s_add_u32 s6, s92, 0x4d00000
	s_addc_u32 s7, s93, 0
	s_cmpk_gt_i32 s26, 0x3fff
	v_lshlrev_b32_e32 v66, 4, v76
	v_cmp_ne_u32_e64 s[4:5], 0, v76
	v_lshlrev_b32_e32 v68, 3, v76
	s_cbranch_scc1 .LBB0_40
	s_ashr_i32 s27, s26, 31
	s_lshl_b64 s[0:1], s[26:27], 13
	v_readlane_b32 s40, v233, 2
	v_readlane_b32 s41, v233, 3
	s_add_u32 s0, s40, s0
	s_addc_u32 s1, s41, s1
	v_mov_b32_e32 v67, 0
	v_lshl_add_u64 v[2:3], s[0:1], 0, v[66:67]
	global_load_dwordx4 v[62:65], v66, s[0:1] nt
	global_load_dwordx4 v[58:61], v66, s[0:1] offset:1024 nt
	global_load_dwordx4 v[54:57], v66, s[0:1] offset:2048 nt
	global_load_dwordx4 v[46:49], v66, s[0:1] offset:3072 nt
	s_movk_i32 s0, 0x1000
	v_add_co_u32_e32 v2, vcc, s0, v2
	s_lshl_b64 s[0:1], s[26:27], 2
	s_nop 0
	v_addc_co_u32_e32 v3, vcc, 0, v3, vcc
	global_load_dwordx4 v[50:53], v[2:3], off nt
	global_load_dwordx4 v[42:45], v[2:3], off offset:1024 nt
	global_load_dwordx4 v[38:41], v[2:3], off offset:2048 nt
	global_load_dwordx4 v[34:37], v[2:3], off offset:3072 nt
	s_add_u32 s8, s92, s0
	v_mov_b32_e32 v69, v67
	s_addc_u32 s9, s93, s1
	s_ashr_i32 s97, s96, 31
	v_lshl_add_u64 v[70:71], s[40:41], 0, v[66:67]
	v_lshl_add_u64 v[72:73], s[6:7], 0, v[68:69]
	s_lshl_b64 s[10:11], s[96:97], 2
	v_mov_b32_e32 v69, 0x358637bd
	s_mov_b32 s17, 0xf800000
	v_mov_b32_e32 v77, 0x260
	s_mov_b64 s[12:13], s[26:27]
	v_readlane_b32 s42, v233, 4
	v_readlane_b32 s43, v233, 5
	v_readlane_b32 s44, v233, 6
	v_readlane_b32 s45, v233, 7
	v_readlane_b32 s46, v233, 8
	v_readlane_b32 s47, v233, 9
	v_readlane_b32 s48, v233, 10
	v_readlane_b32 s49, v233, 11
	v_readlane_b32 s50, v233, 12
	v_readlane_b32 s51, v233, 13
	v_readlane_b32 s52, v233, 14
	v_readlane_b32 s53, v233, 15
	v_readlane_b32 s54, v233, 16
	v_readlane_b32 s55, v233, 17
	s_branch .LBB0_33

.LBB0_128:
	s_or_b64 exec, exec, s[0:1]
	s_bitcmp1_b32 s2, 0
	s_cbranch_scc0 .Ldf_skip_p1
	v_writelane_b32 v234, s0, 0
	v_writelane_b32 v234, s1, 1
	v_writelane_b32 v234, s2, 2
	v_writelane_b32 v234, s3, 3
	v_writelane_b32 v234, s4, 4
	v_writelane_b32 v234, s5, 5
	v_writelane_b32 v234, s6, 6
	v_writelane_b32 v234, s7, 7
	v_writelane_b32 v234, s8, 8
	v_writelane_b32 v234, s9, 9
	v_writelane_b32 v234, s10, 10
	v_writelane_b32 v234, s11, 11
	v_writelane_b32 v234, s12, 12
	v_writelane_b32 v234, s13, 13
	v_writelane_b32 v234, s14, 14
	v_writelane_b32 v234, s15, 15
	v_writelane_b32 v234, s16, 16
	v_writelane_b32 v234, s17, 17
	v_writelane_b32 v234, s18, 18
	v_writelane_b32 v234, s19, 19
	v_writelane_b32 v234, s20, 20
	v_writelane_b32 v234, s21, 21
	v_writelane_b32 v234, s22, 22
	v_writelane_b32 v234, s23, 23
	v_writelane_b32 v234, s24, 24
	v_writelane_b32 v234, s25, 25
	v_writelane_b32 v234, s26, 26
	v_writelane_b32 v234, s27, 27
	v_writelane_b32 v234, s28, 28
	v_writelane_b32 v234, s29, 29
	v_writelane_b32 v234, s30, 30
	v_writelane_b32 v234, s31, 31
	v_writelane_b32 v234, s32, 32
	v_writelane_b32 v234, s33, 33
	v_writelane_b32 v234, s34, 34
	v_writelane_b32 v234, s35, 35
	v_writelane_b32 v234, s36, 36
	v_writelane_b32 v234, s37, 37
	v_writelane_b32 v234, s38, 38
	v_writelane_b32 v234, s39, 39
	v_writelane_b32 v234, s40, 40
	v_writelane_b32 v234, s41, 41
	v_writelane_b32 v234, s42, 42
	v_writelane_b32 v234, s43, 43
	v_writelane_b32 v234, s44, 44
	v_writelane_b32 v234, s45, 45
	v_writelane_b32 v234, s46, 46
	v_writelane_b32 v234, s47, 47
	v_writelane_b32 v234, s48, 48
	v_writelane_b32 v234, s49, 49
	v_writelane_b32 v234, s50, 50
	v_writelane_b32 v234, s51, 51
	v_writelane_b32 v234, s52, 52
	v_writelane_b32 v234, s53, 53
	v_writelane_b32 v234, s54, 54
	v_writelane_b32 v234, s55, 55
	v_writelane_b32 v234, s56, 56
	v_writelane_b32 v234, s57, 57
	v_writelane_b32 v234, s58, 58
	v_writelane_b32 v234, s59, 59
	v_writelane_b32 v234, s60, 60
	v_writelane_b32 v234, s61, 61
	v_writelane_b32 v234, s62, 62
	v_writelane_b32 v234, s63, 63
	v_writelane_b32 v235, s64, 0
	v_writelane_b32 v235, s65, 1
	v_writelane_b32 v235, s66, 2
	v_writelane_b32 v235, s67, 3
	v_writelane_b32 v235, s68, 4
	v_writelane_b32 v235, s69, 5
	v_writelane_b32 v235, s70, 6
	v_writelane_b32 v235, s71, 7
	v_writelane_b32 v235, s72, 8
	v_writelane_b32 v235, s73, 9
	v_writelane_b32 v235, s74, 10
	v_writelane_b32 v235, s75, 11
	v_writelane_b32 v235, s76, 12
	v_writelane_b32 v235, s77, 13
	v_writelane_b32 v235, s78, 14
	v_writelane_b32 v235, s79, 15
	v_writelane_b32 v235, s80, 16
	v_writelane_b32 v235, s81, 17
	v_writelane_b32 v235, s82, 18
	v_writelane_b32 v235, s83, 19
	v_writelane_b32 v235, s84, 20
	v_writelane_b32 v235, s85, 21
	v_writelane_b32 v235, s86, 22
	v_writelane_b32 v235, s87, 23
	v_writelane_b32 v235, s88, 24
	v_writelane_b32 v235, s89, 25
	v_writelane_b32 v235, s90, 26
	v_writelane_b32 v235, s91, 27
	v_writelane_b32 v235, s92, 28
	v_writelane_b32 v235, s93, 29
	v_writelane_b32 v235, s94, 30
	v_writelane_b32 v235, s95, 31
	v_writelane_b32 v235, s96, 32
	v_writelane_b32 v235, s97, 33
	v_writelane_b32 v235, vcc_lo, 34
	v_writelane_b32 v235, vcc_hi, 35
	v_readlane_b32 s72, v233, 47
	v_readlane_b32 s73, v233, 48
	v_readlane_b32 s74, v233, 49
	v_readlane_b32 s75, v233, 50
	v_readlane_b32 s76, v233, 51
	v_readlane_b32 s77, v233, 52
	s_add_u32 s62, s92, 0x400000
	s_addc_u32 s63, s93, 0
	v_mov_b32_e32 v1, v210
	s_nop 0
	v_readfirstlane_b32 s0, v1
	v_and_b32_e32 v76, 63, v1
	s_nop 3
	s_ashr_i32 s8, s0, 6
	s_lshr_b32 s1, s2, 1
	s_lshl_b32 s1, s1, 0
	s_and_b32 s3, s2, 0
	s_or_b32 s1, s1, s3
	s_lshl_b32 s1, s1, 3
	s_add_i32 s26, s8, s1
	s_addk_i32 s26, 0x1000
	s_movk_i32 s96, 0x400
	s_movk_i32 s101, 0x1c7f
	s_mov_b32 s100, 1
	s_branch .Lp0_setup

.LBB0_386:
	s_or_b64 exec, exec, s[0:1]
	s_bitcmp1_b32 s2, 0
	s_cbranch_scc0 .Ldf_skip_p3
	v_writelane_b32 v234, s0, 0
	v_writelane_b32 v234, s1, 1
	v_writelane_b32 v234, s2, 2
	v_writelane_b32 v234, s3, 3
	v_writelane_b32 v234, s4, 4
	v_writelane_b32 v234, s5, 5
	v_writelane_b32 v234, s6, 6
	v_writelane_b32 v234, s7, 7
	v_writelane_b32 v234, s8, 8
	v_writelane_b32 v234, s9, 9
	v_writelane_b32 v234, s10, 10
	v_writelane_b32 v234, s11, 11
	v_writelane_b32 v234, s12, 12
	v_writelane_b32 v234, s13, 13
	v_writelane_b32 v234, s14, 14
	v_writelane_b32 v234, s15, 15
	v_writelane_b32 v234, s16, 16
	v_writelane_b32 v234, s17, 17
	v_writelane_b32 v234, s18, 18
	v_writelane_b32 v234, s19, 19
	v_writelane_b32 v234, s20, 20
	v_writelane_b32 v234, s21, 21
	v_writelane_b32 v234, s22, 22
	v_writelane_b32 v234, s23, 23
	v_writelane_b32 v234, s24, 24
	v_writelane_b32 v234, s25, 25
	v_writelane_b32 v234, s26, 26
	v_writelane_b32 v234, s27, 27
	v_writelane_b32 v234, s28, 28
	v_writelane_b32 v234, s29, 29
	v_writelane_b32 v234, s30, 30
	v_writelane_b32 v234, s31, 31
	v_writelane_b32 v234, s32, 32
	v_writelane_b32 v234, s33, 33
	v_writelane_b32 v234, s34, 34
	v_writelane_b32 v234, s35, 35
	v_writelane_b32 v234, s36, 36
	v_writelane_b32 v234, s37, 37
	v_writelane_b32 v234, s38, 38
	v_writelane_b32 v234, s39, 39
	v_writelane_b32 v234, s40, 40
	v_writelane_b32 v234, s41, 41
	v_writelane_b32 v234, s42, 42
	v_writelane_b32 v234, s43, 43
	v_writelane_b32 v234, s44, 44
	v_writelane_b32 v234, s45, 45
	v_writelane_b32 v234, s46, 46
	v_writelane_b32 v234, s47, 47
	v_writelane_b32 v234, s48, 48
	v_writelane_b32 v234, s49, 49
	v_writelane_b32 v234, s50, 50
	v_writelane_b32 v234, s51, 51
	v_writelane_b32 v234, s52, 52
	v_writelane_b32 v234, s53, 53
	v_writelane_b32 v234, s54, 54
	v_writelane_b32 v234, s55, 55
	v_writelane_b32 v234, s56, 56
	v_writelane_b32 v234, s57, 57
	v_writelane_b32 v234, s58, 58
	v_writelane_b32 v234, s59, 59
	v_writelane_b32 v234, s60, 60
	v_writelane_b32 v234, s61, 61
	v_writelane_b32 v234, s62, 62
	v_writelane_b32 v234, s63, 63
	v_writelane_b32 v235, s64, 0
	v_writelane_b32 v235, s65, 1
	v_writelane_b32 v235, s66, 2
	v_writelane_b32 v235, s67, 3
	v_writelane_b32 v235, s68, 4
	v_writelane_b32 v235, s69, 5
	v_writelane_b32 v235, s70, 6
	v_writelane_b32 v235, s71, 7
	v_writelane_b32 v235, s72, 8
	v_writelane_b32 v235, s73, 9
	v_writelane_b32 v235, s74, 10
	v_writelane_b32 v235, s75, 11
	v_writelane_b32 v235, s76, 12
	v_writelane_b32 v235, s77, 13
	v_writelane_b32 v235, s78, 14
	v_writelane_b32 v235, s79, 15
	v_writelane_b32 v235, s80, 16
	v_writelane_b32 v235, s81, 17
	v_writelane_b32 v235, s82, 18
	v_writelane_b32 v235, s83, 19
	v_writelane_b32 v235, s84, 20
	v_writelane_b32 v235, s85, 21
	v_writelane_b32 v235, s86, 22
	v_writelane_b32 v235, s87, 23
	v_writelane_b32 v235, s88, 24
	v_writelane_b32 v235, s89, 25
	v_writelane_b32 v235, s90, 26
	v_writelane_b32 v235, s91, 27
	v_writelane_b32 v235, s92, 28
	v_writelane_b32 v235, s93, 29
	v_writelane_b32 v235, s94, 30
	v_writelane_b32 v235, s95, 31
	v_writelane_b32 v235, s96, 32
	v_writelane_b32 v235, s97, 33
	v_writelane_b32 v235, vcc_lo, 34
	v_writelane_b32 v235, vcc_hi, 35
	v_readlane_b32 s72, v233, 47
	v_readlane_b32 s73, v233, 48
	v_readlane_b32 s74, v233, 49
	v_readlane_b32 s75, v233, 50
	v_readlane_b32 s76, v233, 51
	v_readlane_b32 s77, v233, 52
	s_add_u32 s62, s92, 0x400000
	s_addc_u32 s63, s93, 0
	v_mov_b32_e32 v1, v210
	s_nop 0
	v_readfirstlane_b32 s0, v1
	v_and_b32_e32 v76, 63, v1
	s_nop 3
	s_ashr_i32 s8, s0, 6
	s_lshr_b32 s1, s2, 1
	s_lshl_b32 s1, s1, 0
	s_and_b32 s3, s2, 0
	s_or_b32 s1, s1, s3
	s_lshl_b32 s1, s1, 3
	s_add_i32 s26, s8, s1
	s_addk_i32 s26, 0x1c80
	s_movk_i32 s96, 0x400
	s_movk_i32 s101, 0x247f
	s_mov_b32 s100, 2
	s_branch .Lp0_setup

.Ldf_skip_p3:
	s_add_u32 s20, s92, 0x11d00000
	s_addc_u32 s21, s93, 0
	s_add_u32 s18, s92, 0x17d00000
	s_addc_u32 s19, s93, 0
	v_mov_b32_e32 v16, v210
	s_waitcnt lgkmcnt(0)
	s_barrier
	s_cmpk_gt_i32 s2, 0x17f
	v_writelane_b32 v232, s78, 52
	v_readfirstlane_b32 s14, v16
	s_nop 0
	v_writelane_b32 v232, s79, 53
	s_cbranch_scc1 .LBB0_406
	v_lshlrev_b32_e32 v0, 4, v16
	v_add_u32_e32 v1, 0x2000, v0
	v_ashrrev_i32_e32 v2, 31, v1
	v_lshrrev_b32_e32 v2, 22, v2
	v_add_u32_e32 v2, v1, v2
	v_ashrrev_i32_e32 v8, 10, v2
	v_mul_i32_i24_e32 v2, 0x400, v8
	v_sub_u32_e32 v1, v1, v2
	v_lshrrev_b32_e32 v2, 4, v1
	v_bitop3_b32 v1, v2, v1, 32 bitop3:0x6c
	v_ashrrev_i32_e32 v2, 31, v1
	v_lshrrev_b32_e32 v2, 26, v2
	v_add_u32_e32 v2, v1, v2
	v_lshlrev_b32_e32 v3, 3, v8
	v_ashrrev_i32_e32 v9, 6, v2
	v_and_b32_e32 v3, -16, v3
	v_add_u32_e32 v3, v9, v3
	v_and_b32_e32 v4, 3, v9
	s_mov_b32 s0, 0x7fffe0
	v_lshrrev_b32_e32 v5, 2, v3
	v_lshlrev_b32_e32 v6, 1, v3
	v_and_b32_e32 v2, 0xc0, v2
	v_and_or_b32 v4, v3, s0, v4
	v_and_b32_e32 v5, 4, v5
	v_and_b32_e32 v6, 24, v6
	v_sub_u32_e32 v1, v1, v2
	v_mov_b32_e32 v2, 1
	v_or3_b32 v4, v4, v5, v6
	v_lshlrev_b32_e32 v5, 5, v8
	v_ashrrev_i16_sdwa v1, v2, sext(v1) dst_sel:DWORD dst_unused:UNUSED_PAD src0_sel:DWORD src1_sel:BYTE_0
	s_movk_i32 s15, 0x600
	v_and_b32_e32 v10, 32, v5
	v_bfe_i32 v11, v1, 0, 16
	v_mul_u32_u24_e32 v4, 0x600, v4
	v_add_u32_e32 v1, v10, v11
	v_mul_lo_u32 v3, v3, s15
	v_add_lshl_u32 v168, v4, v1, 1
	v_add_lshl_u32 v170, v1, v3, 1
	v_bfe_i32 v1, v16, 27, 1
	v_lshrrev_b32_e32 v1, 22, v1
	v_add_u32_e32 v1, v0, v1
	v_and_b32_e32 v1, 0xfffffc00, v1
	v_sub_u32_e32 v0, v0, v1
	v_lshrrev_b32_e32 v1, 4, v0
	v_bitop3_b32 v1, v1, v0, 32 bitop3:0x6c
	v_ashrrev_i32_e32 v0, 31, v0
	v_lshrrev_b32_e32 v0, 26, v0
	v_add_u32_e32 v0, v1, v0
	v_ashrrev_i32_e32 v12, 6, v0
	v_ashrrev_i32_e32 v0, 31, v16
	v_lshrrev_b32_e32 v0, 26, v0
	v_add_u32_e32 v0, v16, v0
	v_ashrrev_i32_e32 v13, 6, v0
	v_lshlrev_b32_e32 v0, 3, v13
	v_and_b32_e32 v0, -16, v0
	s_add_u32 s33, s92, 0x3000000
	v_add_u32_e32 v0, v12, v0
	v_and_b32_e32 v3, 3, v12
	s_addc_u32 s48, s93, 0
	v_and_or_b32 v3, v0, s0, v3
	s_lshr_b32 s0, s3, 29
	s_add_i32 s0, s2, s0
	s_ashr_i32 s22, s14, 6
	s_ashr_i32 s1, s0, 3
	s_and_b32 s0, s0, -8
	s_ashr_i32 s23, s14, 8
	s_lshl_b32 s49, s22, 10
	s_sub_i32 s0, s2, s0
	s_cmp_lt_i32 s0, 0
	s_cselect_b32 s4, 49, 48
	s_mul_i32 s0, s0, s4
	s_add_i32 s0, s0, s1
	s_mul_hi_i32 s1, s0, 0x2aaaaaab
	s_lshr_b32 s4, s1, 31
	s_ashr_i32 s1, s1, 2
	s_add_i32 s1, s1, s4
	s_lshl_b32 s4, s1, 2
	s_mul_i32 s1, s1, 24
	s_sub_i32 s0, s0, s1
	s_bfe_i32 s1, s0, 0x80000
	s_bfe_u32 s1, s1, 0x2000d
	v_lshrrev_b32_e32 v4, 2, v0
	v_lshlrev_b32_e32 v5, 1, v0
	s_add_i32 s1, s0, s1
	v_and_b32_e32 v4, 4, v4
	v_and_b32_e32 v5, 24, v5
	s_bfe_i32 s5, s1, 0x80000
	s_and_b32 s1, s1, 0xfc
	v_or3_b32 v3, v3, v4, v5
	v_lshlrev_b32_e32 v4, 5, v13
	s_sub_i32 s0, s0, s1
	v_and_b32_e32 v14, 32, v4
	v_mul_i32_i24_e32 v4, 64, v12
	s_sext_i32_i16 s5, s5
	s_sext_i32_i8 s0, s0
	v_sub_u32_e32 v1, v1, v4
	s_add_i32 s76, s4, s0
	s_ashr_i32 s0, s5, 2
	v_ashrrev_i16_sdwa v1, v2, sext(v1) dst_sel:DWORD dst_unused:UNUSED_PAD src0_sel:DWORD src1_sel:BYTE_0
	s_lshr_b32 s25, s5, 2
	s_mul_hi_i32 s1, s0, 0xc0000
	s_mul_i32 s0, s0, 0xc0000
	v_bfe_i32 v15, v1, 0, 16
	s_add_u32 s12, s33, s0
	v_mul_u32_u24_e32 v3, 0x600, v3
	v_add_u32_e32 v1, v14, v15
	s_addc_u32 s13, s48, s1
	s_add_i32 s50, s49, 0
	v_add_lshl_u32 v172, v3, v1, 1
	s_add_i32 m0, s50, 0x10000
	s_mul_i32 s4, s76, 0xc0000
	global_load_lds_dwordx4 v172, s[12:13]
	s_add_i32 m0, s50, 0x12000
	s_add_u32 s0, s12, 0x60000
	global_load_lds_dwordx4 v168, s[12:13]
	s_addc_u32 s1, s13, 0
	s_add_i32 m0, s50, 0x14000
	s_mul_hi_i32 s24, s76, 0xc0000
	global_load_lds_dwordx4 v172, s[0:1]
	s_add_i32 m0, s50, 0x16000
	s_add_u32 s4, s20, s4
	v_mul_lo_u32 v0, v0, s15
	s_addc_u32 s5, s21, s24
	s_add_i32 s51, s50, 0x2000
	v_add_lshl_u32 v174, v1, v0, 1
	global_load_lds_dwordx4 v168, s[0:1]
	s_mov_b32 m0, s50
	s_add_u32 s0, s4, 0x60000
	global_load_lds_dwordx4 v174, s[4:5]
	s_mov_b32 m0, s51
	s_addc_u32 s1, s5, 0
	s_add_i32 s52, s50, 0x4000
	global_load_lds_dwordx4 v170, s[4:5]
	s_mov_b32 m0, s52
	s_add_i32 s53, s50, 0x6000
	global_load_lds_dwordx4 v174, s[0:1]
	s_mov_b32 m0, s53
	v_mov_b32_e32 v173, 0
	global_load_lds_dwordx4 v170, s[0:1]
	v_mov_b32_e32 v169, v173
	v_mov_b32_e32 v175, v173
	v_mov_b32_e32 v171, v173
	s_cmp_eq_u32 s23, 1
	s_mov_b32 s62, 0
	v_lshl_add_u64 v[6:7], s[12:13], 0, v[172:173]
	v_lshl_add_u64 v[4:5], s[12:13], 0, v[168:169]
	v_lshl_add_u64 v[2:3], s[4:5], 0, v[174:175]
	v_lshl_add_u64 v[0:1], s[4:5], 0, v[170:171]
	s_cselect_b64 s[0:1], -1, 0
	s_cmp_lg_u32 s23, 1
	s_movk_i32 s24, 0x6000
	s_cbranch_scc1 .LBB0_389
	s_barrier
